# nt hint also on the dilated merge loads, the adaLN weight loads and the first-sublayer x loads
# baseline (speedup 1.0000x reference)
.LBB0_15:
	v_lshl_add_u64 v[140:141], v[26:27], 0, v[34:35]
	v_lshl_add_u64 v[142:143], v[26:27], 0, v[32:33]
	v_lshl_add_u64 v[144:145], v[26:27], 0, v[30:31]
	v_lshl_add_u64 v[146:147], v[26:27], 0, v[28:29]
	global_load_dwordx4 v[76:79], v[140:141], off nt
	global_load_dwordx4 v[80:83], v[142:143], off nt
	global_load_dwordx4 v[84:87], v[144:145], off nt
	global_load_dwordx4 v[88:91], v[146:147], off nt
	v_lshl_add_u64 v[26:27], v[26:27], 0, v[22:23]
	v_lshl_add_u64 v[140:141], v[26:27], 0, v[34:35]
	v_lshl_add_u64 v[142:143], v[26:27], 0, v[32:33]
	v_lshl_add_u64 v[144:145], v[26:27], 0, v[30:31]
	v_lshl_add_u64 v[146:147], v[26:27], 0, v[28:29]
	global_load_dwordx4 v[92:95], v[140:141], off nt
	global_load_dwordx4 v[96:99], v[142:143], off nt
	global_load_dwordx4 v[100:103], v[144:145], off nt
	global_load_dwordx4 v[104:107], v[146:147], off nt
	v_lshl_add_u64 v[26:27], v[26:27], 0, v[22:23]
	v_lshl_add_u64 v[140:141], v[26:27], 0, v[34:35]
	v_lshl_add_u64 v[142:143], v[26:27], 0, v[32:33]
	v_lshl_add_u64 v[144:145], v[26:27], 0, v[30:31]
	v_lshl_add_u64 v[146:147], v[26:27], 0, v[28:29]
	global_load_dwordx4 v[108:111], v[140:141], off nt
	global_load_dwordx4 v[112:115], v[142:143], off nt
	global_load_dwordx4 v[116:119], v[144:145], off nt
	global_load_dwordx4 v[120:123], v[146:147], off nt
	v_lshl_add_u64 v[26:27], v[26:27], 0, v[22:23]
	v_lshl_add_u64 v[140:141], v[26:27], 0, v[34:35]
	v_lshl_add_u64 v[142:143], v[26:27], 0, v[32:33]
	v_lshl_add_u64 v[144:145], v[26:27], 0, v[30:31]
	v_lshl_add_u64 v[146:147], v[26:27], 0, v[28:29]
	global_load_dwordx4 v[124:127], v[140:141], off nt
	global_load_dwordx4 v[128:131], v[142:143], off nt
	global_load_dwordx4 v[132:135], v[144:145], off nt
	global_load_dwordx4 v[136:139], v[146:147], off nt
	v_lshl_add_u64 v[26:27], v[26:27], 0, v[22:23]
	ds_read_b128 v[52:55], v25
	ds_read_b128 v[56:59], v25 offset:4096
	ds_read_b128 v[60:63], v25 offset:8192
	ds_read_b128 v[64:67], v25 offset:12288
	s_waitcnt lgkmcnt(0)
	v_mov_b32_e32 v68, v55
	v_mov_b32_e32 v70, v59
	v_mov_b32_e32 v72, v63
	v_mov_b32_e32 v74, v67
	s_waitcnt vmcnt(15)
	v_pk_fma_f32 v[14:15], v[76:77], v[52:53], v[14:15] op_sel_hi:[1,0,1]
	v_pk_fma_f32 v[16:17], v[78:79], v[52:53], v[16:17] op_sel_hi:[1,0,1]
	v_pk_fma_f32 v[10:11], v[76:77], v[56:57], v[10:11] op_sel_hi:[1,0,1]
	v_pk_fma_f32 v[12:13], v[78:79], v[56:57], v[12:13] op_sel_hi:[1,0,1]
	v_pk_fma_f32 v[6:7], v[76:77], v[60:61], v[6:7] op_sel_hi:[1,0,1]
	v_pk_fma_f32 v[8:9], v[78:79], v[60:61], v[8:9] op_sel_hi:[1,0,1]
	v_pk_fma_f32 v[2:3], v[76:77], v[64:65], v[2:3] op_sel_hi:[1,0,1]
	v_pk_fma_f32 v[4:5], v[78:79], v[64:65], v[4:5] op_sel_hi:[1,0,1]
	s_waitcnt vmcnt(14)
	v_pk_fma_f32 v[14:15], v[80:81], v[52:53], v[14:15] op_sel:[0,1,0]
	v_pk_fma_f32 v[16:17], v[82:83], v[52:53], v[16:17] op_sel:[0,1,0]
	v_pk_fma_f32 v[10:11], v[80:81], v[56:57], v[10:11] op_sel:[0,1,0]
	v_pk_fma_f32 v[12:13], v[82:83], v[56:57], v[12:13] op_sel:[0,1,0]
	v_pk_fma_f32 v[6:7], v[80:81], v[60:61], v[6:7] op_sel:[0,1,0]
	v_pk_fma_f32 v[8:9], v[82:83], v[60:61], v[8:9] op_sel:[0,1,0]
	v_pk_fma_f32 v[2:3], v[80:81], v[64:65], v[2:3] op_sel:[0,1,0]
	v_pk_fma_f32 v[4:5], v[82:83], v[64:65], v[4:5] op_sel:[0,1,0]
	s_waitcnt vmcnt(13)
	v_pk_fma_f32 v[14:15], v[84:85], v[54:55], v[14:15] op_sel_hi:[1,0,1]
	v_pk_fma_f32 v[16:17], v[86:87], v[54:55], v[16:17] op_sel_hi:[1,0,1]
	v_pk_fma_f32 v[10:11], v[84:85], v[58:59], v[10:11] op_sel_hi:[1,0,1]
	v_pk_fma_f32 v[12:13], v[86:87], v[58:59], v[12:13] op_sel_hi:[1,0,1]
	v_pk_fma_f32 v[6:7], v[84:85], v[62:63], v[6:7] op_sel_hi:[1,0,1]
	v_pk_fma_f32 v[8:9], v[86:87], v[62:63], v[8:9] op_sel_hi:[1,0,1]
	v_pk_fma_f32 v[2:3], v[84:85], v[66:67], v[2:3] op_sel_hi:[1,0,1]
	v_pk_fma_f32 v[4:5], v[86:87], v[66:67], v[4:5] op_sel_hi:[1,0,1]
	s_waitcnt vmcnt(12)
	v_pk_fma_f32 v[14:15], v[88:89], v[68:69], v[14:15] op_sel_hi:[1,0,1]
	v_pk_fma_f32 v[16:17], v[90:91], v[68:69], v[16:17] op_sel_hi:[1,0,1]
	v_pk_fma_f32 v[10:11], v[88:89], v[70:71], v[10:11] op_sel_hi:[1,0,1]
	v_pk_fma_f32 v[12:13], v[90:91], v[70:71], v[12:13] op_sel_hi:[1,0,1]
	v_pk_fma_f32 v[6:7], v[88:89], v[72:73], v[6:7] op_sel_hi:[1,0,1]
	v_pk_fma_f32 v[8:9], v[90:91], v[72:73], v[8:9] op_sel_hi:[1,0,1]
	v_pk_fma_f32 v[2:3], v[88:89], v[74:75], v[2:3] op_sel_hi:[1,0,1]
	v_pk_fma_f32 v[4:5], v[90:91], v[74:75], v[4:5] op_sel_hi:[1,0,1]
	v_lshl_add_u64 v[140:141], v[26:27], 0, v[34:35]
	v_lshl_add_u64 v[142:143], v[26:27], 0, v[32:33]
	v_lshl_add_u64 v[144:145], v[26:27], 0, v[30:31]
	v_lshl_add_u64 v[146:147], v[26:27], 0, v[28:29]
	global_load_dwordx4 v[76:79], v[140:141], off nt
	global_load_dwordx4 v[80:83], v[142:143], off nt
	global_load_dwordx4 v[84:87], v[144:145], off nt
	global_load_dwordx4 v[88:91], v[146:147], off nt
	v_lshl_add_u64 v[26:27], v[26:27], 0, v[22:23]
	ds_read_b128 v[52:55], v25 offset:16
	ds_read_b128 v[56:59], v25 offset:4112
	ds_read_b128 v[60:63], v25 offset:8208
	ds_read_b128 v[64:67], v25 offset:12304
	s_waitcnt lgkmcnt(0)
	v_mov_b32_e32 v68, v55
	v_mov_b32_e32 v70, v59
	v_mov_b32_e32 v72, v63
	v_mov_b32_e32 v74, v67
	s_waitcnt vmcnt(15)
	v_pk_fma_f32 v[14:15], v[92:93], v[52:53], v[14:15] op_sel_hi:[1,0,1]
	v_pk_fma_f32 v[16:17], v[94:95], v[52:53], v[16:17] op_sel_hi:[1,0,1]
	v_pk_fma_f32 v[10:11], v[92:93], v[56:57], v[10:11] op_sel_hi:[1,0,1]
	v_pk_fma_f32 v[12:13], v[94:95], v[56:57], v[12:13] op_sel_hi:[1,0,1]
	v_pk_fma_f32 v[6:7], v[92:93], v[60:61], v[6:7] op_sel_hi:[1,0,1]
	v_pk_fma_f32 v[8:9], v[94:95], v[60:61], v[8:9] op_sel_hi:[1,0,1]
	v_pk_fma_f32 v[2:3], v[92:93], v[64:65], v[2:3] op_sel_hi:[1,0,1]
	v_pk_fma_f32 v[4:5], v[94:95], v[64:65], v[4:5] op_sel_hi:[1,0,1]
	s_waitcnt vmcnt(14)
	v_pk_fma_f32 v[14:15], v[96:97], v[52:53], v[14:15] op_sel:[0,1,0]
	v_pk_fma_f32 v[16:17], v[98:99], v[52:53], v[16:17] op_sel:[0,1,0]
	v_pk_fma_f32 v[10:11], v[96:97], v[56:57], v[10:11] op_sel:[0,1,0]
	v_pk_fma_f32 v[12:13], v[98:99], v[56:57], v[12:13] op_sel:[0,1,0]
	v_pk_fma_f32 v[6:7], v[96:97], v[60:61], v[6:7] op_sel:[0,1,0]
	v_pk_fma_f32 v[8:9], v[98:99], v[60:61], v[8:9] op_sel:[0,1,0]
	v_pk_fma_f32 v[2:3], v[96:97], v[64:65], v[2:3] op_sel:[0,1,0]
	v_pk_fma_f32 v[4:5], v[98:99], v[64:65], v[4:5] op_sel:[0,1,0]
	s_waitcnt vmcnt(13)
	v_pk_fma_f32 v[14:15], v[100:101], v[54:55], v[14:15] op_sel_hi:[1,0,1]
	v_pk_fma_f32 v[16:17], v[102:103], v[54:55], v[16:17] op_sel_hi:[1,0,1]
	v_pk_fma_f32 v[10:11], v[100:101], v[58:59], v[10:11] op_sel_hi:[1,0,1]
	v_pk_fma_f32 v[12:13], v[102:103], v[58:59], v[12:13] op_sel_hi:[1,0,1]
	v_pk_fma_f32 v[6:7], v[100:101], v[62:63], v[6:7] op_sel_hi:[1,0,1]
	v_pk_fma_f32 v[8:9], v[102:103], v[62:63], v[8:9] op_sel_hi:[1,0,1]
	v_pk_fma_f32 v[2:3], v[100:101], v[66:67], v[2:3] op_sel_hi:[1,0,1]
	v_pk_fma_f32 v[4:5], v[102:103], v[66:67], v[4:5] op_sel_hi:[1,0,1]
	s_waitcnt vmcnt(12)
	v_pk_fma_f32 v[14:15], v[104:105], v[68:69], v[14:15] op_sel_hi:[1,0,1]
	v_pk_fma_f32 v[16:17], v[106:107], v[68:69], v[16:17] op_sel_hi:[1,0,1]
	v_pk_fma_f32 v[10:11], v[104:105], v[70:71], v[10:11] op_sel_hi:[1,0,1]
	v_pk_fma_f32 v[12:13], v[106:107], v[70:71], v[12:13] op_sel_hi:[1,0,1]
	v_pk_fma_f32 v[6:7], v[104:105], v[72:73], v[6:7] op_sel_hi:[1,0,1]
	v_pk_fma_f32 v[8:9], v[106:107], v[72:73], v[8:9] op_sel_hi:[1,0,1]
	v_pk_fma_f32 v[2:3], v[104:105], v[74:75], v[2:3] op_sel_hi:[1,0,1]
	v_pk_fma_f32 v[4:5], v[106:107], v[74:75], v[4:5] op_sel_hi:[1,0,1]
	v_lshl_add_u64 v[140:141], v[26:27], 0, v[34:35]
	v_lshl_add_u64 v[142:143], v[26:27], 0, v[32:33]
	v_lshl_add_u64 v[144:145], v[26:27], 0, v[30:31]
	v_lshl_add_u64 v[146:147], v[26:27], 0, v[28:29]
	global_load_dwordx4 v[92:95], v[140:141], off nt
	global_load_dwordx4 v[96:99], v[142:143], off nt
	global_load_dwordx4 v[100:103], v[144:145], off nt
	global_load_dwordx4 v[104:107], v[146:147], off nt
	v_lshl_add_u64 v[26:27], v[26:27], 0, v[22:23]
	ds_read_b128 v[52:55], v25 offset:32
	ds_read_b128 v[56:59], v25 offset:4128
	ds_read_b128 v[60:63], v25 offset:8224
	ds_read_b128 v[64:67], v25 offset:12320
	s_waitcnt lgkmcnt(0)
	v_mov_b32_e32 v68, v55
	v_mov_b32_e32 v70, v59
	v_mov_b32_e32 v72, v63
	v_mov_b32_e32 v74, v67
	s_waitcnt vmcnt(15)
	v_pk_fma_f32 v[14:15], v[108:109], v[52:53], v[14:15] op_sel_hi:[1,0,1]
	v_pk_fma_f32 v[16:17], v[110:111], v[52:53], v[16:17] op_sel_hi:[1,0,1]
	v_pk_fma_f32 v[10:11], v[108:109], v[56:57], v[10:11] op_sel_hi:[1,0,1]
	v_pk_fma_f32 v[12:13], v[110:111], v[56:57], v[12:13] op_sel_hi:[1,0,1]
	v_pk_fma_f32 v[6:7], v[108:109], v[60:61], v[6:7] op_sel_hi:[1,0,1]
	v_pk_fma_f32 v[8:9], v[110:111], v[60:61], v[8:9] op_sel_hi:[1,0,1]
	v_pk_fma_f32 v[2:3], v[108:109], v[64:65], v[2:3] op_sel_hi:[1,0,1]
	v_pk_fma_f32 v[4:5], v[110:111], v[64:65], v[4:5] op_sel_hi:[1,0,1]
	s_waitcnt vmcnt(14)
	v_pk_fma_f32 v[14:15], v[112:113], v[52:53], v[14:15] op_sel:[0,1,0]
	v_pk_fma_f32 v[16:17], v[114:115], v[52:53], v[16:17] op_sel:[0,1,0]
	v_pk_fma_f32 v[10:11], v[112:113], v[56:57], v[10:11] op_sel:[0,1,0]
	v_pk_fma_f32 v[12:13], v[114:115], v[56:57], v[12:13] op_sel:[0,1,0]
	v_pk_fma_f32 v[6:7], v[112:113], v[60:61], v[6:7] op_sel:[0,1,0]
	v_pk_fma_f32 v[8:9], v[114:115], v[60:61], v[8:9] op_sel:[0,1,0]
	v_pk_fma_f32 v[2:3], v[112:113], v[64:65], v[2:3] op_sel:[0,1,0]
	v_pk_fma_f32 v[4:5], v[114:115], v[64:65], v[4:5] op_sel:[0,1,0]
	s_waitcnt vmcnt(13)
	v_pk_fma_f32 v[14:15], v[116:117], v[54:55], v[14:15] op_sel_hi:[1,0,1]
	v_pk_fma_f32 v[16:17], v[118:119], v[54:55], v[16:17] op_sel_hi:[1,0,1]
	v_pk_fma_f32 v[10:11], v[116:117], v[58:59], v[10:11] op_sel_hi:[1,0,1]
	v_pk_fma_f32 v[12:13], v[118:119], v[58:59], v[12:13] op_sel_hi:[1,0,1]
	v_pk_fma_f32 v[6:7], v[116:117], v[62:63], v[6:7] op_sel_hi:[1,0,1]
	v_pk_fma_f32 v[8:9], v[118:119], v[62:63], v[8:9] op_sel_hi:[1,0,1]
	v_pk_fma_f32 v[2:3], v[116:117], v[66:67], v[2:3] op_sel_hi:[1,0,1]
	v_pk_fma_f32 v[4:5], v[118:119], v[66:67], v[4:5] op_sel_hi:[1,0,1]
	s_waitcnt vmcnt(12)
	v_pk_fma_f32 v[14:15], v[120:121], v[68:69], v[14:15] op_sel_hi:[1,0,1]
	v_pk_fma_f32 v[16:17], v[122:123], v[68:69], v[16:17] op_sel_hi:[1,0,1]
	v_pk_fma_f32 v[10:11], v[120:121], v[70:71], v[10:11] op_sel_hi:[1,0,1]
	v_pk_fma_f32 v[12:13], v[122:123], v[70:71], v[12:13] op_sel_hi:[1,0,1]
	v_pk_fma_f32 v[6:7], v[120:121], v[72:73], v[6:7] op_sel_hi:[1,0,1]
	v_pk_fma_f32 v[8:9], v[122:123], v[72:73], v[8:9] op_sel_hi:[1,0,1]
	v_pk_fma_f32 v[2:3], v[120:121], v[74:75], v[2:3] op_sel_hi:[1,0,1]
	v_pk_fma_f32 v[4:5], v[122:123], v[74:75], v[4:5] op_sel_hi:[1,0,1]
	v_lshl_add_u64 v[140:141], v[26:27], 0, v[34:35]
	v_lshl_add_u64 v[142:143], v[26:27], 0, v[32:33]
	v_lshl_add_u64 v[144:145], v[26:27], 0, v[30:31]
	v_lshl_add_u64 v[146:147], v[26:27], 0, v[28:29]
	global_load_dwordx4 v[108:111], v[140:141], off nt
	global_load_dwordx4 v[112:115], v[142:143], off nt
	global_load_dwordx4 v[116:119], v[144:145], off nt
	global_load_dwordx4 v[120:123], v[146:147], off nt
	v_lshl_add_u64 v[26:27], v[26:27], 0, v[22:23]
	ds_read_b128 v[52:55], v25 offset:48
	ds_read_b128 v[56:59], v25 offset:4144
	ds_read_b128 v[60:63], v25 offset:8240
	ds_read_b128 v[64:67], v25 offset:12336
	s_waitcnt lgkmcnt(0)
	v_mov_b32_e32 v68, v55
	v_mov_b32_e32 v70, v59
	v_mov_b32_e32 v72, v63
	v_mov_b32_e32 v74, v67
	s_waitcnt vmcnt(15)
	v_pk_fma_f32 v[14:15], v[124:125], v[52:53], v[14:15] op_sel_hi:[1,0,1]
	v_pk_fma_f32 v[16:17], v[126:127], v[52:53], v[16:17] op_sel_hi:[1,0,1]
	v_pk_fma_f32 v[10:11], v[124:125], v[56:57], v[10:11] op_sel_hi:[1,0,1]
	v_pk_fma_f32 v[12:13], v[126:127], v[56:57], v[12:13] op_sel_hi:[1,0,1]
	v_pk_fma_f32 v[6:7], v[124:125], v[60:61], v[6:7] op_sel_hi:[1,0,1]
	v_pk_fma_f32 v[8:9], v[126:127], v[60:61], v[8:9] op_sel_hi:[1,0,1]
	v_pk_fma_f32 v[2:3], v[124:125], v[64:65], v[2:3] op_sel_hi:[1,0,1]
	v_pk_fma_f32 v[4:5], v[126:127], v[64:65], v[4:5] op_sel_hi:[1,0,1]
	s_waitcnt vmcnt(14)
	v_pk_fma_f32 v[14:15], v[128:129], v[52:53], v[14:15] op_sel:[0,1,0]
	v_pk_fma_f32 v[16:17], v[130:131], v[52:53], v[16:17] op_sel:[0,1,0]
	v_pk_fma_f32 v[10:11], v[128:129], v[56:57], v[10:11] op_sel:[0,1,0]
	v_pk_fma_f32 v[12:13], v[130:131], v[56:57], v[12:13] op_sel:[0,1,0]
	v_pk_fma_f32 v[6:7], v[128:129], v[60:61], v[6:7] op_sel:[0,1,0]
	v_pk_fma_f32 v[8:9], v[130:131], v[60:61], v[8:9] op_sel:[0,1,0]
	v_pk_fma_f32 v[2:3], v[128:129], v[64:65], v[2:3] op_sel:[0,1,0]
	v_pk_fma_f32 v[4:5], v[130:131], v[64:65], v[4:5] op_sel:[0,1,0]
	s_waitcnt vmcnt(13)
	v_pk_fma_f32 v[14:15], v[132:133], v[54:55], v[14:15] op_sel_hi:[1,0,1]
	v_pk_fma_f32 v[16:17], v[134:135], v[54:55], v[16:17] op_sel_hi:[1,0,1]
	v_pk_fma_f32 v[10:11], v[132:133], v[58:59], v[10:11] op_sel_hi:[1,0,1]
	v_pk_fma_f32 v[12:13], v[134:135], v[58:59], v[12:13] op_sel_hi:[1,0,1]
	v_pk_fma_f32 v[6:7], v[132:133], v[62:63], v[6:7] op_sel_hi:[1,0,1]
	v_pk_fma_f32 v[8:9], v[134:135], v[62:63], v[8:9] op_sel_hi:[1,0,1]
	v_pk_fma_f32 v[2:3], v[132:133], v[66:67], v[2:3] op_sel_hi:[1,0,1]
	v_pk_fma_f32 v[4:5], v[134:135], v[66:67], v[4:5] op_sel_hi:[1,0,1]
	s_waitcnt vmcnt(12)
	v_pk_fma_f32 v[14:15], v[136:137], v[68:69], v[14:15] op_sel_hi:[1,0,1]
	v_pk_fma_f32 v[16:17], v[138:139], v[68:69], v[16:17] op_sel_hi:[1,0,1]
	v_pk_fma_f32 v[10:11], v[136:137], v[70:71], v[10:11] op_sel_hi:[1,0,1]
	v_pk_fma_f32 v[12:13], v[138:139], v[70:71], v[12:13] op_sel_hi:[1,0,1]
	v_pk_fma_f32 v[6:7], v[136:137], v[72:73], v[6:7] op_sel_hi:[1,0,1]
	v_pk_fma_f32 v[8:9], v[138:139], v[72:73], v[8:9] op_sel_hi:[1,0,1]
	v_pk_fma_f32 v[2:3], v[136:137], v[74:75], v[2:3] op_sel_hi:[1,0,1]
	v_pk_fma_f32 v[4:5], v[138:139], v[74:75], v[4:5] op_sel_hi:[1,0,1]
	v_lshl_add_u64 v[140:141], v[26:27], 0, v[34:35]
	v_lshl_add_u64 v[142:143], v[26:27], 0, v[32:33]
	v_lshl_add_u64 v[144:145], v[26:27], 0, v[30:31]
	v_lshl_add_u64 v[146:147], v[26:27], 0, v[28:29]
	global_load_dwordx4 v[124:127], v[140:141], off nt
	global_load_dwordx4 v[128:131], v[142:143], off nt
	global_load_dwordx4 v[132:135], v[144:145], off nt
	global_load_dwordx4 v[136:139], v[146:147], off nt
	v_lshl_add_u64 v[26:27], v[26:27], 0, v[22:23]
	ds_read_b128 v[52:55], v25 offset:64
	ds_read_b128 v[56:59], v25 offset:4160
	ds_read_b128 v[60:63], v25 offset:8256
	ds_read_b128 v[64:67], v25 offset:12352
	s_waitcnt lgkmcnt(0)
	v_mov_b32_e32 v68, v55
	v_mov_b32_e32 v70, v59
	v_mov_b32_e32 v72, v63
	v_mov_b32_e32 v74, v67
	s_waitcnt vmcnt(15)
	v_pk_fma_f32 v[14:15], v[76:77], v[52:53], v[14:15] op_sel_hi:[1,0,1]
	v_pk_fma_f32 v[16:17], v[78:79], v[52:53], v[16:17] op_sel_hi:[1,0,1]
	v_pk_fma_f32 v[10:11], v[76:77], v[56:57], v[10:11] op_sel_hi:[1,0,1]
	v_pk_fma_f32 v[12:13], v[78:79], v[56:57], v[12:13] op_sel_hi:[1,0,1]
	v_pk_fma_f32 v[6:7], v[76:77], v[60:61], v[6:7] op_sel_hi:[1,0,1]
	v_pk_fma_f32 v[8:9], v[78:79], v[60:61], v[8:9] op_sel_hi:[1,0,1]
	v_pk_fma_f32 v[2:3], v[76:77], v[64:65], v[2:3] op_sel_hi:[1,0,1]
	v_pk_fma_f32 v[4:5], v[78:79], v[64:65], v[4:5] op_sel_hi:[1,0,1]
	s_waitcnt vmcnt(14)
	v_pk_fma_f32 v[14:15], v[80:81], v[52:53], v[14:15] op_sel:[0,1,0]
	v_pk_fma_f32 v[16:17], v[82:83], v[52:53], v[16:17] op_sel:[0,1,0]
	v_pk_fma_f32 v[10:11], v[80:81], v[56:57], v[10:11] op_sel:[0,1,0]
	v_pk_fma_f32 v[12:13], v[82:83], v[56:57], v[12:13] op_sel:[0,1,0]
	v_pk_fma_f32 v[6:7], v[80:81], v[60:61], v[6:7] op_sel:[0,1,0]
	v_pk_fma_f32 v[8:9], v[82:83], v[60:61], v[8:9] op_sel:[0,1,0]
	v_pk_fma_f32 v[2:3], v[80:81], v[64:65], v[2:3] op_sel:[0,1,0]
	v_pk_fma_f32 v[4:5], v[82:83], v[64:65], v[4:5] op_sel:[0,1,0]
	s_waitcnt vmcnt(13)
	v_pk_fma_f32 v[14:15], v[84:85], v[54:55], v[14:15] op_sel_hi:[1,0,1]
	v_pk_fma_f32 v[16:17], v[86:87], v[54:55], v[16:17] op_sel_hi:[1,0,1]
	v_pk_fma_f32 v[10:11], v[84:85], v[58:59], v[10:11] op_sel_hi:[1,0,1]
	v_pk_fma_f32 v[12:13], v[86:87], v[58:59], v[12:13] op_sel_hi:[1,0,1]
	v_pk_fma_f32 v[6:7], v[84:85], v[62:63], v[6:7] op_sel_hi:[1,0,1]
	v_pk_fma_f32 v[8:9], v[86:87], v[62:63], v[8:9] op_sel_hi:[1,0,1]
	v_pk_fma_f32 v[2:3], v[84:85], v[66:67], v[2:3] op_sel_hi:[1,0,1]
	v_pk_fma_f32 v[4:5], v[86:87], v[66:67], v[4:5] op_sel_hi:[1,0,1]
	s_waitcnt vmcnt(12)
	v_pk_fma_f32 v[14:15], v[88:89], v[68:69], v[14:15] op_sel_hi:[1,0,1]
	v_pk_fma_f32 v[16:17], v[90:91], v[68:69], v[16:17] op_sel_hi:[1,0,1]
	v_pk_fma_f32 v[10:11], v[88:89], v[70:71], v[10:11] op_sel_hi:[1,0,1]
	v_pk_fma_f32 v[12:13], v[90:91], v[70:71], v[12:13] op_sel_hi:[1,0,1]
	v_pk_fma_f32 v[6:7], v[88:89], v[72:73], v[6:7] op_sel_hi:[1,0,1]
	v_pk_fma_f32 v[8:9], v[90:91], v[72:73], v[8:9] op_sel_hi:[1,0,1]
	v_pk_fma_f32 v[2:3], v[88:89], v[74:75], v[2:3] op_sel_hi:[1,0,1]
	v_pk_fma_f32 v[4:5], v[90:91], v[74:75], v[4:5] op_sel_hi:[1,0,1]
	v_lshl_add_u64 v[140:141], v[26:27], 0, v[34:35]
	v_lshl_add_u64 v[142:143], v[26:27], 0, v[32:33]
	v_lshl_add_u64 v[144:145], v[26:27], 0, v[30:31]
	v_lshl_add_u64 v[146:147], v[26:27], 0, v[28:29]
	global_load_dwordx4 v[76:79], v[140:141], off nt
	global_load_dwordx4 v[80:83], v[142:143], off nt
	global_load_dwordx4 v[84:87], v[144:145], off nt
	global_load_dwordx4 v[88:91], v[146:147], off nt
	v_lshl_add_u64 v[26:27], v[26:27], 0, v[22:23]
	ds_read_b128 v[52:55], v25 offset:80
	ds_read_b128 v[56:59], v25 offset:4176
	ds_read_b128 v[60:63], v25 offset:8272
	ds_read_b128 v[64:67], v25 offset:12368
	s_waitcnt lgkmcnt(0)
	v_mov_b32_e32 v68, v55
	v_mov_b32_e32 v70, v59
	v_mov_b32_e32 v72, v63
	v_mov_b32_e32 v74, v67
	s_waitcnt vmcnt(15)
	v_pk_fma_f32 v[14:15], v[92:93], v[52:53], v[14:15] op_sel_hi:[1,0,1]
	v_pk_fma_f32 v[16:17], v[94:95], v[52:53], v[16:17] op_sel_hi:[1,0,1]
	v_pk_fma_f32 v[10:11], v[92:93], v[56:57], v[10:11] op_sel_hi:[1,0,1]
	v_pk_fma_f32 v[12:13], v[94:95], v[56:57], v[12:13] op_sel_hi:[1,0,1]
	v_pk_fma_f32 v[6:7], v[92:93], v[60:61], v[6:7] op_sel_hi:[1,0,1]
	v_pk_fma_f32 v[8:9], v[94:95], v[60:61], v[8:9] op_sel_hi:[1,0,1]
	v_pk_fma_f32 v[2:3], v[92:93], v[64:65], v[2:3] op_sel_hi:[1,0,1]
	v_pk_fma_f32 v[4:5], v[94:95], v[64:65], v[4:5] op_sel_hi:[1,0,1]
	s_waitcnt vmcnt(14)
	v_pk_fma_f32 v[14:15], v[96:97], v[52:53], v[14:15] op_sel:[0,1,0]
	v_pk_fma_f32 v[16:17], v[98:99], v[52:53], v[16:17] op_sel:[0,1,0]
	v_pk_fma_f32 v[10:11], v[96:97], v[56:57], v[10:11] op_sel:[0,1,0]
	v_pk_fma_f32 v[12:13], v[98:99], v[56:57], v[12:13] op_sel:[0,1,0]
	v_pk_fma_f32 v[6:7], v[96:97], v[60:61], v[6:7] op_sel:[0,1,0]
	v_pk_fma_f32 v[8:9], v[98:99], v[60:61], v[8:9] op_sel:[0,1,0]
	v_pk_fma_f32 v[2:3], v[96:97], v[64:65], v[2:3] op_sel:[0,1,0]
	v_pk_fma_f32 v[4:5], v[98:99], v[64:65], v[4:5] op_sel:[0,1,0]
	s_waitcnt vmcnt(13)
	v_pk_fma_f32 v[14:15], v[100:101], v[54:55], v[14:15] op_sel_hi:[1,0,1]
	v_pk_fma_f32 v[16:17], v[102:103], v[54:55], v[16:17] op_sel_hi:[1,0,1]
	v_pk_fma_f32 v[10:11], v[100:101], v[58:59], v[10:11] op_sel_hi:[1,0,1]
	v_pk_fma_f32 v[12:13], v[102:103], v[58:59], v[12:13] op_sel_hi:[1,0,1]
	v_pk_fma_f32 v[6:7], v[100:101], v[62:63], v[6:7] op_sel_hi:[1,0,1]
	v_pk_fma_f32 v[8:9], v[102:103], v[62:63], v[8:9] op_sel_hi:[1,0,1]
	v_pk_fma_f32 v[2:3], v[100:101], v[66:67], v[2:3] op_sel_hi:[1,0,1]
	v_pk_fma_f32 v[4:5], v[102:103], v[66:67], v[4:5] op_sel_hi:[1,0,1]
	s_waitcnt vmcnt(12)
	v_pk_fma_f32 v[14:15], v[104:105], v[68:69], v[14:15] op_sel_hi:[1,0,1]
	v_pk_fma_f32 v[16:17], v[106:107], v[68:69], v[16:17] op_sel_hi:[1,0,1]
	v_pk_fma_f32 v[10:11], v[104:105], v[70:71], v[10:11] op_sel_hi:[1,0,1]
	v_pk_fma_f32 v[12:13], v[106:107], v[70:71], v[12:13] op_sel_hi:[1,0,1]
	v_pk_fma_f32 v[6:7], v[104:105], v[72:73], v[6:7] op_sel_hi:[1,0,1]
	v_pk_fma_f32 v[8:9], v[106:107], v[72:73], v[8:9] op_sel_hi:[1,0,1]
	v_pk_fma_f32 v[2:3], v[104:105], v[74:75], v[2:3] op_sel_hi:[1,0,1]
	v_pk_fma_f32 v[4:5], v[106:107], v[74:75], v[4:5] op_sel_hi:[1,0,1]
	v_lshl_add_u64 v[140:141], v[26:27], 0, v[34:35]
	v_lshl_add_u64 v[142:143], v[26:27], 0, v[32:33]
	v_lshl_add_u64 v[144:145], v[26:27], 0, v[30:31]
	v_lshl_add_u64 v[146:147], v[26:27], 0, v[28:29]
	global_load_dwordx4 v[92:95], v[140:141], off nt
	global_load_dwordx4 v[96:99], v[142:143], off nt
	global_load_dwordx4 v[100:103], v[144:145], off nt
	global_load_dwordx4 v[104:107], v[146:147], off nt
	v_lshl_add_u64 v[26:27], v[26:27], 0, v[22:23]
	ds_read_b128 v[52:55], v25 offset:96
	ds_read_b128 v[56:59], v25 offset:4192
	ds_read_b128 v[60:63], v25 offset:8288
	ds_read_b128 v[64:67], v25 offset:12384
	s_waitcnt lgkmcnt(0)
	v_mov_b32_e32 v68, v55
	v_mov_b32_e32 v70, v59
	v_mov_b32_e32 v72, v63
	v_mov_b32_e32 v74, v67
	s_waitcnt vmcnt(15)
	v_pk_fma_f32 v[14:15], v[108:109], v[52:53], v[14:15] op_sel_hi:[1,0,1]
	v_pk_fma_f32 v[16:17], v[110:111], v[52:53], v[16:17] op_sel_hi:[1,0,1]
	v_pk_fma_f32 v[10:11], v[108:109], v[56:57], v[10:11] op_sel_hi:[1,0,1]
	v_pk_fma_f32 v[12:13], v[110:111], v[56:57], v[12:13] op_sel_hi:[1,0,1]
	v_pk_fma_f32 v[6:7], v[108:109], v[60:61], v[6:7] op_sel_hi:[1,0,1]
	v_pk_fma_f32 v[8:9], v[110:111], v[60:61], v[8:9] op_sel_hi:[1,0,1]
	v_pk_fma_f32 v[2:3], v[108:109], v[64:65], v[2:3] op_sel_hi:[1,0,1]
	v_pk_fma_f32 v[4:5], v[110:111], v[64:65], v[4:5] op_sel_hi:[1,0,1]
	s_waitcnt vmcnt(14)
	v_pk_fma_f32 v[14:15], v[112:113], v[52:53], v[14:15] op_sel:[0,1,0]
	v_pk_fma_f32 v[16:17], v[114:115], v[52:53], v[16:17] op_sel:[0,1,0]
	v_pk_fma_f32 v[10:11], v[112:113], v[56:57], v[10:11] op_sel:[0,1,0]
	v_pk_fma_f32 v[12:13], v[114:115], v[56:57], v[12:13] op_sel:[0,1,0]
	v_pk_fma_f32 v[6:7], v[112:113], v[60:61], v[6:7] op_sel:[0,1,0]
	v_pk_fma_f32 v[8:9], v[114:115], v[60:61], v[8:9] op_sel:[0,1,0]
	v_pk_fma_f32 v[2:3], v[112:113], v[64:65], v[2:3] op_sel:[0,1,0]
	v_pk_fma_f32 v[4:5], v[114:115], v[64:65], v[4:5] op_sel:[0,1,0]
	s_waitcnt vmcnt(13)
	v_pk_fma_f32 v[14:15], v[116:117], v[54:55], v[14:15] op_sel_hi:[1,0,1]
	v_pk_fma_f32 v[16:17], v[118:119], v[54:55], v[16:17] op_sel_hi:[1,0,1]
	v_pk_fma_f32 v[10:11], v[116:117], v[58:59], v[10:11] op_sel_hi:[1,0,1]
	v_pk_fma_f32 v[12:13], v[118:119], v[58:59], v[12:13] op_sel_hi:[1,0,1]
	v_pk_fma_f32 v[6:7], v[116:117], v[62:63], v[6:7] op_sel_hi:[1,0,1]
	v_pk_fma_f32 v[8:9], v[118:119], v[62:63], v[8:9] op_sel_hi:[1,0,1]
	v_pk_fma_f32 v[2:3], v[116:117], v[66:67], v[2:3] op_sel_hi:[1,0,1]
	v_pk_fma_f32 v[4:5], v[118:119], v[66:67], v[4:5] op_sel_hi:[1,0,1]
	s_waitcnt vmcnt(12)
	v_pk_fma_f32 v[14:15], v[120:121], v[68:69], v[14:15] op_sel_hi:[1,0,1]
	v_pk_fma_f32 v[16:17], v[122:123], v[68:69], v[16:17] op_sel_hi:[1,0,1]
	v_pk_fma_f32 v[10:11], v[120:121], v[70:71], v[10:11] op_sel_hi:[1,0,1]
	v_pk_fma_f32 v[12:13], v[122:123], v[70:71], v[12:13] op_sel_hi:[1,0,1]
	v_pk_fma_f32 v[6:7], v[120:121], v[72:73], v[6:7] op_sel_hi:[1,0,1]
	v_pk_fma_f32 v[8:9], v[122:123], v[72:73], v[8:9] op_sel_hi:[1,0,1]
	v_pk_fma_f32 v[2:3], v[120:121], v[74:75], v[2:3] op_sel_hi:[1,0,1]
	v_pk_fma_f32 v[4:5], v[122:123], v[74:75], v[4:5] op_sel_hi:[1,0,1]
	v_lshl_add_u64 v[140:141], v[26:27], 0, v[34:35]
	v_lshl_add_u64 v[142:143], v[26:27], 0, v[32:33]
	v_lshl_add_u64 v[144:145], v[26:27], 0, v[30:31]
	v_lshl_add_u64 v[146:147], v[26:27], 0, v[28:29]
	global_load_dwordx4 v[108:111], v[140:141], off nt
	global_load_dwordx4 v[112:115], v[142:143], off nt
	global_load_dwordx4 v[116:119], v[144:145], off nt
	global_load_dwordx4 v[120:123], v[146:147], off nt
	v_lshl_add_u64 v[26:27], v[26:27], 0, v[22:23]
	ds_read_b128 v[52:55], v25 offset:112
	ds_read_b128 v[56:59], v25 offset:4208
	ds_read_b128 v[60:63], v25 offset:8304
	ds_read_b128 v[64:67], v25 offset:12400
	s_waitcnt lgkmcnt(0)
	v_mov_b32_e32 v68, v55
	v_mov_b32_e32 v70, v59
	v_mov_b32_e32 v72, v63
	v_mov_b32_e32 v74, v67
	s_waitcnt vmcnt(15)
	v_pk_fma_f32 v[14:15], v[124:125], v[52:53], v[14:15] op_sel_hi:[1,0,1]
	v_pk_fma_f32 v[16:17], v[126:127], v[52:53], v[16:17] op_sel_hi:[1,0,1]
	v_pk_fma_f32 v[10:11], v[124:125], v[56:57], v[10:11] op_sel_hi:[1,0,1]
	v_pk_fma_f32 v[12:13], v[126:127], v[56:57], v[12:13] op_sel_hi:[1,0,1]
	v_pk_fma_f32 v[6:7], v[124:125], v[60:61], v[6:7] op_sel_hi:[1,0,1]
	v_pk_fma_f32 v[8:9], v[126:127], v[60:61], v[8:9] op_sel_hi:[1,0,1]
	v_pk_fma_f32 v[2:3], v[124:125], v[64:65], v[2:3] op_sel_hi:[1,0,1]
	v_pk_fma_f32 v[4:5], v[126:127], v[64:65], v[4:5] op_sel_hi:[1,0,1]
	s_waitcnt vmcnt(14)
	v_pk_fma_f32 v[14:15], v[128:129], v[52:53], v[14:15] op_sel:[0,1,0]
	v_pk_fma_f32 v[16:17], v[130:131], v[52:53], v[16:17] op_sel:[0,1,0]
	v_pk_fma_f32 v[10:11], v[128:129], v[56:57], v[10:11] op_sel:[0,1,0]
	v_pk_fma_f32 v[12:13], v[130:131], v[56:57], v[12:13] op_sel:[0,1,0]
	v_pk_fma_f32 v[6:7], v[128:129], v[60:61], v[6:7] op_sel:[0,1,0]
	v_pk_fma_f32 v[8:9], v[130:131], v[60:61], v[8:9] op_sel:[0,1,0]
	v_pk_fma_f32 v[2:3], v[128:129], v[64:65], v[2:3] op_sel:[0,1,0]
	v_pk_fma_f32 v[4:5], v[130:131], v[64:65], v[4:5] op_sel:[0,1,0]
	s_waitcnt vmcnt(13)
	v_pk_fma_f32 v[14:15], v[132:133], v[54:55], v[14:15] op_sel_hi:[1,0,1]
	v_pk_fma_f32 v[16:17], v[134:135], v[54:55], v[16:17] op_sel_hi:[1,0,1]
	v_pk_fma_f32 v[10:11], v[132:133], v[58:59], v[10:11] op_sel_hi:[1,0,1]
	v_pk_fma_f32 v[12:13], v[134:135], v[58:59], v[12:13] op_sel_hi:[1,0,1]
	v_pk_fma_f32 v[6:7], v[132:133], v[62:63], v[6:7] op_sel_hi:[1,0,1]
	v_pk_fma_f32 v[8:9], v[134:135], v[62:63], v[8:9] op_sel_hi:[1,0,1]
	v_pk_fma_f32 v[2:3], v[132:133], v[66:67], v[2:3] op_sel_hi:[1,0,1]
	v_pk_fma_f32 v[4:5], v[134:135], v[66:67], v[4:5] op_sel_hi:[1,0,1]
	s_waitcnt vmcnt(12)
	v_pk_fma_f32 v[14:15], v[136:137], v[68:69], v[14:15] op_sel_hi:[1,0,1]
	v_pk_fma_f32 v[16:17], v[138:139], v[68:69], v[16:17] op_sel_hi:[1,0,1]
	v_pk_fma_f32 v[10:11], v[136:137], v[70:71], v[10:11] op_sel_hi:[1,0,1]
	v_pk_fma_f32 v[12:13], v[138:139], v[70:71], v[12:13] op_sel_hi:[1,0,1]
	v_pk_fma_f32 v[6:7], v[136:137], v[72:73], v[6:7] op_sel_hi:[1,0,1]
	v_pk_fma_f32 v[8:9], v[138:139], v[72:73], v[8:9] op_sel_hi:[1,0,1]
	v_pk_fma_f32 v[2:3], v[136:137], v[74:75], v[2:3] op_sel_hi:[1,0,1]
	v_pk_fma_f32 v[4:5], v[138:139], v[74:75], v[4:5] op_sel_hi:[1,0,1]
	v_lshl_add_u64 v[140:141], v[26:27], 0, v[34:35]
	v_lshl_add_u64 v[142:143], v[26:27], 0, v[32:33]
	v_lshl_add_u64 v[144:145], v[26:27], 0, v[30:31]
	v_lshl_add_u64 v[146:147], v[26:27], 0, v[28:29]
	global_load_dwordx4 v[124:127], v[140:141], off nt
	global_load_dwordx4 v[128:131], v[142:143], off nt
	global_load_dwordx4 v[132:135], v[144:145], off nt
	global_load_dwordx4 v[136:139], v[146:147], off nt
	v_lshl_add_u64 v[26:27], v[26:27], 0, v[22:23]
	ds_read_b128 v[52:55], v25 offset:128
	ds_read_b128 v[56:59], v25 offset:4224
	ds_read_b128 v[60:63], v25 offset:8320
	ds_read_b128 v[64:67], v25 offset:12416
	s_waitcnt lgkmcnt(0)
	v_mov_b32_e32 v68, v55
	v_mov_b32_e32 v70, v59
	v_mov_b32_e32 v72, v63
	v_mov_b32_e32 v74, v67
	s_waitcnt vmcnt(15)
	v_pk_fma_f32 v[14:15], v[76:77], v[52:53], v[14:15] op_sel_hi:[1,0,1]
	v_pk_fma_f32 v[16:17], v[78:79], v[52:53], v[16:17] op_sel_hi:[1,0,1]
	v_pk_fma_f32 v[10:11], v[76:77], v[56:57], v[10:11] op_sel_hi:[1,0,1]
	v_pk_fma_f32 v[12:13], v[78:79], v[56:57], v[12:13] op_sel_hi:[1,0,1]
	v_pk_fma_f32 v[6:7], v[76:77], v[60:61], v[6:7] op_sel_hi:[1,0,1]
	v_pk_fma_f32 v[8:9], v[78:79], v[60:61], v[8:9] op_sel_hi:[1,0,1]
	v_pk_fma_f32 v[2:3], v[76:77], v[64:65], v[2:3] op_sel_hi:[1,0,1]
	v_pk_fma_f32 v[4:5], v[78:79], v[64:65], v[4:5] op_sel_hi:[1,0,1]
	s_waitcnt vmcnt(14)
	v_pk_fma_f32 v[14:15], v[80:81], v[52:53], v[14:15] op_sel:[0,1,0]
	v_pk_fma_f32 v[16:17], v[82:83], v[52:53], v[16:17] op_sel:[0,1,0]
	v_pk_fma_f32 v[10:11], v[80:81], v[56:57], v[10:11] op_sel:[0,1,0]
	v_pk_fma_f32 v[12:13], v[82:83], v[56:57], v[12:13] op_sel:[0,1,0]
	v_pk_fma_f32 v[6:7], v[80:81], v[60:61], v[6:7] op_sel:[0,1,0]
	v_pk_fma_f32 v[8:9], v[82:83], v[60:61], v[8:9] op_sel:[0,1,0]
	v_pk_fma_f32 v[2:3], v[80:81], v[64:65], v[2:3] op_sel:[0,1,0]
	v_pk_fma_f32 v[4:5], v[82:83], v[64:65], v[4:5] op_sel:[0,1,0]
	s_waitcnt vmcnt(13)
	v_pk_fma_f32 v[14:15], v[84:85], v[54:55], v[14:15] op_sel_hi:[1,0,1]
	v_pk_fma_f32 v[16:17], v[86:87], v[54:55], v[16:17] op_sel_hi:[1,0,1]
	v_pk_fma_f32 v[10:11], v[84:85], v[58:59], v[10:11] op_sel_hi:[1,0,1]
	v_pk_fma_f32 v[12:13], v[86:87], v[58:59], v[12:13] op_sel_hi:[1,0,1]
	v_pk_fma_f32 v[6:7], v[84:85], v[62:63], v[6:7] op_sel_hi:[1,0,1]
	v_pk_fma_f32 v[8:9], v[86:87], v[62:63], v[8:9] op_sel_hi:[1,0,1]
	v_pk_fma_f32 v[2:3], v[84:85], v[66:67], v[2:3] op_sel_hi:[1,0,1]
	v_pk_fma_f32 v[4:5], v[86:87], v[66:67], v[4:5] op_sel_hi:[1,0,1]
	s_waitcnt vmcnt(12)
	v_pk_fma_f32 v[14:15], v[88:89], v[68:69], v[14:15] op_sel_hi:[1,0,1]
	v_pk_fma_f32 v[16:17], v[90:91], v[68:69], v[16:17] op_sel_hi:[1,0,1]
	v_pk_fma_f32 v[10:11], v[88:89], v[70:71], v[10:11] op_sel_hi:[1,0,1]
	v_pk_fma_f32 v[12:13], v[90:91], v[70:71], v[12:13] op_sel_hi:[1,0,1]
	v_pk_fma_f32 v[6:7], v[88:89], v[72:73], v[6:7] op_sel_hi:[1,0,1]
	v_pk_fma_f32 v[8:9], v[90:91], v[72:73], v[8:9] op_sel_hi:[1,0,1]
	v_pk_fma_f32 v[2:3], v[88:89], v[74:75], v[2:3] op_sel_hi:[1,0,1]
	v_pk_fma_f32 v[4:5], v[90:91], v[74:75], v[4:5] op_sel_hi:[1,0,1]
	v_lshl_add_u64 v[140:141], v[26:27], 0, v[34:35]
	v_lshl_add_u64 v[142:143], v[26:27], 0, v[32:33]
	v_lshl_add_u64 v[144:145], v[26:27], 0, v[30:31]
	v_lshl_add_u64 v[146:147], v[26:27], 0, v[28:29]
	global_load_dwordx4 v[76:79], v[140:141], off nt
	global_load_dwordx4 v[80:83], v[142:143], off nt
	global_load_dwordx4 v[84:87], v[144:145], off nt
	global_load_dwordx4 v[88:91], v[146:147], off nt
	v_lshl_add_u64 v[26:27], v[26:27], 0, v[22:23]
	ds_read_b128 v[52:55], v25 offset:144
	ds_read_b128 v[56:59], v25 offset:4240
	ds_read_b128 v[60:63], v25 offset:8336
	ds_read_b128 v[64:67], v25 offset:12432
	s_waitcnt lgkmcnt(0)
	v_mov_b32_e32 v68, v55
	v_mov_b32_e32 v70, v59
	v_mov_b32_e32 v72, v63
	v_mov_b32_e32 v74, v67
	s_waitcnt vmcnt(15)
	v_pk_fma_f32 v[14:15], v[92:93], v[52:53], v[14:15] op_sel_hi:[1,0,1]
	v_pk_fma_f32 v[16:17], v[94:95], v[52:53], v[16:17] op_sel_hi:[1,0,1]
	v_pk_fma_f32 v[10:11], v[92:93], v[56:57], v[10:11] op_sel_hi:[1,0,1]
	v_pk_fma_f32 v[12:13], v[94:95], v[56:57], v[12:13] op_sel_hi:[1,0,1]
	v_pk_fma_f32 v[6:7], v[92:93], v[60:61], v[6:7] op_sel_hi:[1,0,1]
	v_pk_fma_f32 v[8:9], v[94:95], v[60:61], v[8:9] op_sel_hi:[1,0,1]
	v_pk_fma_f32 v[2:3], v[92:93], v[64:65], v[2:3] op_sel_hi:[1,0,1]
	v_pk_fma_f32 v[4:5], v[94:95], v[64:65], v[4:5] op_sel_hi:[1,0,1]
	s_waitcnt vmcnt(14)
	v_pk_fma_f32 v[14:15], v[96:97], v[52:53], v[14:15] op_sel:[0,1,0]
	v_pk_fma_f32 v[16:17], v[98:99], v[52:53], v[16:17] op_sel:[0,1,0]
	v_pk_fma_f32 v[10:11], v[96:97], v[56:57], v[10:11] op_sel:[0,1,0]
	v_pk_fma_f32 v[12:13], v[98:99], v[56:57], v[12:13] op_sel:[0,1,0]
	v_pk_fma_f32 v[6:7], v[96:97], v[60:61], v[6:7] op_sel:[0,1,0]
	v_pk_fma_f32 v[8:9], v[98:99], v[60:61], v[8:9] op_sel:[0,1,0]
	v_pk_fma_f32 v[2:3], v[96:97], v[64:65], v[2:3] op_sel:[0,1,0]
	v_pk_fma_f32 v[4:5], v[98:99], v[64:65], v[4:5] op_sel:[0,1,0]
	s_waitcnt vmcnt(13)
	v_pk_fma_f32 v[14:15], v[100:101], v[54:55], v[14:15] op_sel_hi:[1,0,1]
	v_pk_fma_f32 v[16:17], v[102:103], v[54:55], v[16:17] op_sel_hi:[1,0,1]
	v_pk_fma_f32 v[10:11], v[100:101], v[58:59], v[10:11] op_sel_hi:[1,0,1]
	v_pk_fma_f32 v[12:13], v[102:103], v[58:59], v[12:13] op_sel_hi:[1,0,1]
	v_pk_fma_f32 v[6:7], v[100:101], v[62:63], v[6:7] op_sel_hi:[1,0,1]
	v_pk_fma_f32 v[8:9], v[102:103], v[62:63], v[8:9] op_sel_hi:[1,0,1]
	v_pk_fma_f32 v[2:3], v[100:101], v[66:67], v[2:3] op_sel_hi:[1,0,1]
	v_pk_fma_f32 v[4:5], v[102:103], v[66:67], v[4:5] op_sel_hi:[1,0,1]
	s_waitcnt vmcnt(12)
	v_pk_fma_f32 v[14:15], v[104:105], v[68:69], v[14:15] op_sel_hi:[1,0,1]
	v_pk_fma_f32 v[16:17], v[106:107], v[68:69], v[16:17] op_sel_hi:[1,0,1]
	v_pk_fma_f32 v[10:11], v[104:105], v[70:71], v[10:11] op_sel_hi:[1,0,1]
	v_pk_fma_f32 v[12:13], v[106:107], v[70:71], v[12:13] op_sel_hi:[1,0,1]
	v_pk_fma_f32 v[6:7], v[104:105], v[72:73], v[6:7] op_sel_hi:[1,0,1]
	v_pk_fma_f32 v[8:9], v[106:107], v[72:73], v[8:9] op_sel_hi:[1,0,1]
	v_pk_fma_f32 v[2:3], v[104:105], v[74:75], v[2:3] op_sel_hi:[1,0,1]
	v_pk_fma_f32 v[4:5], v[106:107], v[74:75], v[4:5] op_sel_hi:[1,0,1]
	v_lshl_add_u64 v[140:141], v[26:27], 0, v[34:35]
	v_lshl_add_u64 v[142:143], v[26:27], 0, v[32:33]
	v_lshl_add_u64 v[144:145], v[26:27], 0, v[30:31]
	v_lshl_add_u64 v[146:147], v[26:27], 0, v[28:29]
	global_load_dwordx4 v[92:95], v[140:141], off nt
	global_load_dwordx4 v[96:99], v[142:143], off nt
	global_load_dwordx4 v[100:103], v[144:145], off nt
	global_load_dwordx4 v[104:107], v[146:147], off nt
	v_lshl_add_u64 v[26:27], v[26:27], 0, v[22:23]
	ds_read_b128 v[52:55], v25 offset:160
	ds_read_b128 v[56:59], v25 offset:4256
	ds_read_b128 v[60:63], v25 offset:8352
	ds_read_b128 v[64:67], v25 offset:12448
	s_waitcnt lgkmcnt(0)
	v_mov_b32_e32 v68, v55
	v_mov_b32_e32 v70, v59
	v_mov_b32_e32 v72, v63
	v_mov_b32_e32 v74, v67
	s_waitcnt vmcnt(15)
	v_pk_fma_f32 v[14:15], v[108:109], v[52:53], v[14:15] op_sel_hi:[1,0,1]
	v_pk_fma_f32 v[16:17], v[110:111], v[52:53], v[16:17] op_sel_hi:[1,0,1]
	v_pk_fma_f32 v[10:11], v[108:109], v[56:57], v[10:11] op_sel_hi:[1,0,1]
	v_pk_fma_f32 v[12:13], v[110:111], v[56:57], v[12:13] op_sel_hi:[1,0,1]
	v_pk_fma_f32 v[6:7], v[108:109], v[60:61], v[6:7] op_sel_hi:[1,0,1]
	v_pk_fma_f32 v[8:9], v[110:111], v[60:61], v[8:9] op_sel_hi:[1,0,1]
	v_pk_fma_f32 v[2:3], v[108:109], v[64:65], v[2:3] op_sel_hi:[1,0,1]
	v_pk_fma_f32 v[4:5], v[110:111], v[64:65], v[4:5] op_sel_hi:[1,0,1]
	s_waitcnt vmcnt(14)
	v_pk_fma_f32 v[14:15], v[112:113], v[52:53], v[14:15] op_sel:[0,1,0]
	v_pk_fma_f32 v[16:17], v[114:115], v[52:53], v[16:17] op_sel:[0,1,0]
	v_pk_fma_f32 v[10:11], v[112:113], v[56:57], v[10:11] op_sel:[0,1,0]
	v_pk_fma_f32 v[12:13], v[114:115], v[56:57], v[12:13] op_sel:[0,1,0]
	v_pk_fma_f32 v[6:7], v[112:113], v[60:61], v[6:7] op_sel:[0,1,0]
	v_pk_fma_f32 v[8:9], v[114:115], v[60:61], v[8:9] op_sel:[0,1,0]
	v_pk_fma_f32 v[2:3], v[112:113], v[64:65], v[2:3] op_sel:[0,1,0]
	v_pk_fma_f32 v[4:5], v[114:115], v[64:65], v[4:5] op_sel:[0,1,0]
	s_waitcnt vmcnt(13)
	v_pk_fma_f32 v[14:15], v[116:117], v[54:55], v[14:15] op_sel_hi:[1,0,1]
	v_pk_fma_f32 v[16:17], v[118:119], v[54:55], v[16:17] op_sel_hi:[1,0,1]
	v_pk_fma_f32 v[10:11], v[116:117], v[58:59], v[10:11] op_sel_hi:[1,0,1]
	v_pk_fma_f32 v[12:13], v[118:119], v[58:59], v[12:13] op_sel_hi:[1,0,1]
	v_pk_fma_f32 v[6:7], v[116:117], v[62:63], v[6:7] op_sel_hi:[1,0,1]
	v_pk_fma_f32 v[8:9], v[118:119], v[62:63], v[8:9] op_sel_hi:[1,0,1]
	v_pk_fma_f32 v[2:3], v[116:117], v[66:67], v[2:3] op_sel_hi:[1,0,1]
	v_pk_fma_f32 v[4:5], v[118:119], v[66:67], v[4:5] op_sel_hi:[1,0,1]
	s_waitcnt vmcnt(12)
	v_pk_fma_f32 v[14:15], v[120:121], v[68:69], v[14:15] op_sel_hi:[1,0,1]
	v_pk_fma_f32 v[16:17], v[122:123], v[68:69], v[16:17] op_sel_hi:[1,0,1]
	v_pk_fma_f32 v[10:11], v[120:121], v[70:71], v[10:11] op_sel_hi:[1,0,1]
	v_pk_fma_f32 v[12:13], v[122:123], v[70:71], v[12:13] op_sel_hi:[1,0,1]
	v_pk_fma_f32 v[6:7], v[120:121], v[72:73], v[6:7] op_sel_hi:[1,0,1]
	v_pk_fma_f32 v[8:9], v[122:123], v[72:73], v[8:9] op_sel_hi:[1,0,1]
	v_pk_fma_f32 v[2:3], v[120:121], v[74:75], v[2:3] op_sel_hi:[1,0,1]
	v_pk_fma_f32 v[4:5], v[122:123], v[74:75], v[4:5] op_sel_hi:[1,0,1]
	v_lshl_add_u64 v[140:141], v[26:27], 0, v[34:35]
	v_lshl_add_u64 v[142:143], v[26:27], 0, v[32:33]
	v_lshl_add_u64 v[144:145], v[26:27], 0, v[30:31]
	v_lshl_add_u64 v[146:147], v[26:27], 0, v[28:29]
	global_load_dwordx4 v[108:111], v[140:141], off nt
	global_load_dwordx4 v[112:115], v[142:143], off nt
	global_load_dwordx4 v[116:119], v[144:145], off nt
	global_load_dwordx4 v[120:123], v[146:147], off nt
	v_lshl_add_u64 v[26:27], v[26:27], 0, v[22:23]
	ds_read_b128 v[52:55], v25 offset:176
	ds_read_b128 v[56:59], v25 offset:4272
	ds_read_b128 v[60:63], v25 offset:8368
	ds_read_b128 v[64:67], v25 offset:12464
	s_waitcnt lgkmcnt(0)
	v_mov_b32_e32 v68, v55
	v_mov_b32_e32 v70, v59
	v_mov_b32_e32 v72, v63
	v_mov_b32_e32 v74, v67
	s_waitcnt vmcnt(15)
	v_pk_fma_f32 v[14:15], v[124:125], v[52:53], v[14:15] op_sel_hi:[1,0,1]
	v_pk_fma_f32 v[16:17], v[126:127], v[52:53], v[16:17] op_sel_hi:[1,0,1]
	v_pk_fma_f32 v[10:11], v[124:125], v[56:57], v[10:11] op_sel_hi:[1,0,1]
	v_pk_fma_f32 v[12:13], v[126:127], v[56:57], v[12:13] op_sel_hi:[1,0,1]
	v_pk_fma_f32 v[6:7], v[124:125], v[60:61], v[6:7] op_sel_hi:[1,0,1]
	v_pk_fma_f32 v[8:9], v[126:127], v[60:61], v[8:9] op_sel_hi:[1,0,1]
	v_pk_fma_f32 v[2:3], v[124:125], v[64:65], v[2:3] op_sel_hi:[1,0,1]
	v_pk_fma_f32 v[4:5], v[126:127], v[64:65], v[4:5] op_sel_hi:[1,0,1]
	s_waitcnt vmcnt(14)
	v_pk_fma_f32 v[14:15], v[128:129], v[52:53], v[14:15] op_sel:[0,1,0]
	v_pk_fma_f32 v[16:17], v[130:131], v[52:53], v[16:17] op_sel:[0,1,0]
	v_pk_fma_f32 v[10:11], v[128:129], v[56:57], v[10:11] op_sel:[0,1,0]
	v_pk_fma_f32 v[12:13], v[130:131], v[56:57], v[12:13] op_sel:[0,1,0]
	v_pk_fma_f32 v[6:7], v[128:129], v[60:61], v[6:7] op_sel:[0,1,0]
	v_pk_fma_f32 v[8:9], v[130:131], v[60:61], v[8:9] op_sel:[0,1,0]
	v_pk_fma_f32 v[2:3], v[128:129], v[64:65], v[2:3] op_sel:[0,1,0]
	v_pk_fma_f32 v[4:5], v[130:131], v[64:65], v[4:5] op_sel:[0,1,0]
	s_waitcnt vmcnt(13)
	v_pk_fma_f32 v[14:15], v[132:133], v[54:55], v[14:15] op_sel_hi:[1,0,1]
	v_pk_fma_f32 v[16:17], v[134:135], v[54:55], v[16:17] op_sel_hi:[1,0,1]
	v_pk_fma_f32 v[10:11], v[132:133], v[58:59], v[10:11] op_sel_hi:[1,0,1]
	v_pk_fma_f32 v[12:13], v[134:135], v[58:59], v[12:13] op_sel_hi:[1,0,1]
	v_pk_fma_f32 v[6:7], v[132:133], v[62:63], v[6:7] op_sel_hi:[1,0,1]
	v_pk_fma_f32 v[8:9], v[134:135], v[62:63], v[8:9] op_sel_hi:[1,0,1]
	v_pk_fma_f32 v[2:3], v[132:133], v[66:67], v[2:3] op_sel_hi:[1,0,1]
	v_pk_fma_f32 v[4:5], v[134:135], v[66:67], v[4:5] op_sel_hi:[1,0,1]
	s_waitcnt vmcnt(12)
	v_pk_fma_f32 v[14:15], v[136:137], v[68:69], v[14:15] op_sel_hi:[1,0,1]
	v_pk_fma_f32 v[16:17], v[138:139], v[68:69], v[16:17] op_sel_hi:[1,0,1]
	v_pk_fma_f32 v[10:11], v[136:137], v[70:71], v[10:11] op_sel_hi:[1,0,1]
	v_pk_fma_f32 v[12:13], v[138:139], v[70:71], v[12:13] op_sel_hi:[1,0,1]
	v_pk_fma_f32 v[6:7], v[136:137], v[72:73], v[6:7] op_sel_hi:[1,0,1]
	v_pk_fma_f32 v[8:9], v[138:139], v[72:73], v[8:9] op_sel_hi:[1,0,1]
	v_pk_fma_f32 v[2:3], v[136:137], v[74:75], v[2:3] op_sel_hi:[1,0,1]
	v_pk_fma_f32 v[4:5], v[138:139], v[74:75], v[4:5] op_sel_hi:[1,0,1]
	v_lshl_add_u64 v[140:141], v[26:27], 0, v[34:35]
	v_lshl_add_u64 v[142:143], v[26:27], 0, v[32:33]
	v_lshl_add_u64 v[144:145], v[26:27], 0, v[30:31]
	v_lshl_add_u64 v[146:147], v[26:27], 0, v[28:29]
	global_load_dwordx4 v[124:127], v[140:141], off nt
	global_load_dwordx4 v[128:131], v[142:143], off nt
	global_load_dwordx4 v[132:135], v[144:145], off nt
	global_load_dwordx4 v[136:139], v[146:147], off nt
	v_lshl_add_u64 v[26:27], v[26:27], 0, v[22:23]
	ds_read_b128 v[52:55], v25 offset:192
	ds_read_b128 v[56:59], v25 offset:4288
	ds_read_b128 v[60:63], v25 offset:8384
	ds_read_b128 v[64:67], v25 offset:12480
	s_waitcnt lgkmcnt(0)
	v_mov_b32_e32 v68, v55
	v_mov_b32_e32 v70, v59
	v_mov_b32_e32 v72, v63
	v_mov_b32_e32 v74, v67
	s_waitcnt vmcnt(15)
	v_pk_fma_f32 v[14:15], v[76:77], v[52:53], v[14:15] op_sel_hi:[1,0,1]
	v_pk_fma_f32 v[16:17], v[78:79], v[52:53], v[16:17] op_sel_hi:[1,0,1]
	v_pk_fma_f32 v[10:11], v[76:77], v[56:57], v[10:11] op_sel_hi:[1,0,1]
	v_pk_fma_f32 v[12:13], v[78:79], v[56:57], v[12:13] op_sel_hi:[1,0,1]
	v_pk_fma_f32 v[6:7], v[76:77], v[60:61], v[6:7] op_sel_hi:[1,0,1]
	v_pk_fma_f32 v[8:9], v[78:79], v[60:61], v[8:9] op_sel_hi:[1,0,1]
	v_pk_fma_f32 v[2:3], v[76:77], v[64:65], v[2:3] op_sel_hi:[1,0,1]
	v_pk_fma_f32 v[4:5], v[78:79], v[64:65], v[4:5] op_sel_hi:[1,0,1]
	s_waitcnt vmcnt(14)
	v_pk_fma_f32 v[14:15], v[80:81], v[52:53], v[14:15] op_sel:[0,1,0]
	v_pk_fma_f32 v[16:17], v[82:83], v[52:53], v[16:17] op_sel:[0,1,0]
	v_pk_fma_f32 v[10:11], v[80:81], v[56:57], v[10:11] op_sel:[0,1,0]
	v_pk_fma_f32 v[12:13], v[82:83], v[56:57], v[12:13] op_sel:[0,1,0]
	v_pk_fma_f32 v[6:7], v[80:81], v[60:61], v[6:7] op_sel:[0,1,0]
	v_pk_fma_f32 v[8:9], v[82:83], v[60:61], v[8:9] op_sel:[0,1,0]
	v_pk_fma_f32 v[2:3], v[80:81], v[64:65], v[2:3] op_sel:[0,1,0]
	v_pk_fma_f32 v[4:5], v[82:83], v[64:65], v[4:5] op_sel:[0,1,0]
	s_waitcnt vmcnt(13)
	v_pk_fma_f32 v[14:15], v[84:85], v[54:55], v[14:15] op_sel_hi:[1,0,1]
	v_pk_fma_f32 v[16:17], v[86:87], v[54:55], v[16:17] op_sel_hi:[1,0,1]
	v_pk_fma_f32 v[10:11], v[84:85], v[58:59], v[10:11] op_sel_hi:[1,0,1]
	v_pk_fma_f32 v[12:13], v[86:87], v[58:59], v[12:13] op_sel_hi:[1,0,1]
	v_pk_fma_f32 v[6:7], v[84:85], v[62:63], v[6:7] op_sel_hi:[1,0,1]
	v_pk_fma_f32 v[8:9], v[86:87], v[62:63], v[8:9] op_sel_hi:[1,0,1]
	v_pk_fma_f32 v[2:3], v[84:85], v[66:67], v[2:3] op_sel_hi:[1,0,1]
	v_pk_fma_f32 v[4:5], v[86:87], v[66:67], v[4:5] op_sel_hi:[1,0,1]
	s_waitcnt vmcnt(12)
	v_pk_fma_f32 v[14:15], v[88:89], v[68:69], v[14:15] op_sel_hi:[1,0,1]
	v_pk_fma_f32 v[16:17], v[90:91], v[68:69], v[16:17] op_sel_hi:[1,0,1]
	v_pk_fma_f32 v[10:11], v[88:89], v[70:71], v[10:11] op_sel_hi:[1,0,1]
	v_pk_fma_f32 v[12:13], v[90:91], v[70:71], v[12:13] op_sel_hi:[1,0,1]
	v_pk_fma_f32 v[6:7], v[88:89], v[72:73], v[6:7] op_sel_hi:[1,0,1]
	v_pk_fma_f32 v[8:9], v[90:91], v[72:73], v[8:9] op_sel_hi:[1,0,1]
	v_pk_fma_f32 v[2:3], v[88:89], v[74:75], v[2:3] op_sel_hi:[1,0,1]
	v_pk_fma_f32 v[4:5], v[90:91], v[74:75], v[4:5] op_sel_hi:[1,0,1]
	ds_read_b128 v[52:55], v25 offset:208
	ds_read_b128 v[56:59], v25 offset:4304
	ds_read_b128 v[60:63], v25 offset:8400
	ds_read_b128 v[64:67], v25 offset:12496
	s_waitcnt lgkmcnt(0)
	v_mov_b32_e32 v68, v55
	v_mov_b32_e32 v70, v59
	v_mov_b32_e32 v72, v63
	v_mov_b32_e32 v74, v67
	s_waitcnt vmcnt(11)
	v_pk_fma_f32 v[14:15], v[92:93], v[52:53], v[14:15] op_sel_hi:[1,0,1]
	v_pk_fma_f32 v[16:17], v[94:95], v[52:53], v[16:17] op_sel_hi:[1,0,1]
	v_pk_fma_f32 v[10:11], v[92:93], v[56:57], v[10:11] op_sel_hi:[1,0,1]
	v_pk_fma_f32 v[12:13], v[94:95], v[56:57], v[12:13] op_sel_hi:[1,0,1]
	v_pk_fma_f32 v[6:7], v[92:93], v[60:61], v[6:7] op_sel_hi:[1,0,1]
	v_pk_fma_f32 v[8:9], v[94:95], v[60:61], v[8:9] op_sel_hi:[1,0,1]
	v_pk_fma_f32 v[2:3], v[92:93], v[64:65], v[2:3] op_sel_hi:[1,0,1]
	v_pk_fma_f32 v[4:5], v[94:95], v[64:65], v[4:5] op_sel_hi:[1,0,1]
	s_waitcnt vmcnt(10)
	v_pk_fma_f32 v[14:15], v[96:97], v[52:53], v[14:15] op_sel:[0,1,0]
	v_pk_fma_f32 v[16:17], v[98:99], v[52:53], v[16:17] op_sel:[0,1,0]
	v_pk_fma_f32 v[10:11], v[96:97], v[56:57], v[10:11] op_sel:[0,1,0]
	v_pk_fma_f32 v[12:13], v[98:99], v[56:57], v[12:13] op_sel:[0,1,0]
	v_pk_fma_f32 v[6:7], v[96:97], v[60:61], v[6:7] op_sel:[0,1,0]
	v_pk_fma_f32 v[8:9], v[98:99], v[60:61], v[8:9] op_sel:[0,1,0]
	v_pk_fma_f32 v[2:3], v[96:97], v[64:65], v[2:3] op_sel:[0,1,0]
	v_pk_fma_f32 v[4:5], v[98:99], v[64:65], v[4:5] op_sel:[0,1,0]
	s_waitcnt vmcnt(9)
	v_pk_fma_f32 v[14:15], v[100:101], v[54:55], v[14:15] op_sel_hi:[1,0,1]
	v_pk_fma_f32 v[16:17], v[102:103], v[54:55], v[16:17] op_sel_hi:[1,0,1]
	v_pk_fma_f32 v[10:11], v[100:101], v[58:59], v[10:11] op_sel_hi:[1,0,1]
	v_pk_fma_f32 v[12:13], v[102:103], v[58:59], v[12:13] op_sel_hi:[1,0,1]
	v_pk_fma_f32 v[6:7], v[100:101], v[62:63], v[6:7] op_sel_hi:[1,0,1]
	v_pk_fma_f32 v[8:9], v[102:103], v[62:63], v[8:9] op_sel_hi:[1,0,1]
	v_pk_fma_f32 v[2:3], v[100:101], v[66:67], v[2:3] op_sel_hi:[1,0,1]
	v_pk_fma_f32 v[4:5], v[102:103], v[66:67], v[4:5] op_sel_hi:[1,0,1]
	s_waitcnt vmcnt(8)
	v_pk_fma_f32 v[14:15], v[104:105], v[68:69], v[14:15] op_sel_hi:[1,0,1]
	v_pk_fma_f32 v[16:17], v[106:107], v[68:69], v[16:17] op_sel_hi:[1,0,1]
	v_pk_fma_f32 v[10:11], v[104:105], v[70:71], v[10:11] op_sel_hi:[1,0,1]
	v_pk_fma_f32 v[12:13], v[106:107], v[70:71], v[12:13] op_sel_hi:[1,0,1]
	v_pk_fma_f32 v[6:7], v[104:105], v[72:73], v[6:7] op_sel_hi:[1,0,1]
	v_pk_fma_f32 v[8:9], v[106:107], v[72:73], v[8:9] op_sel_hi:[1,0,1]
	v_pk_fma_f32 v[2:3], v[104:105], v[74:75], v[2:3] op_sel_hi:[1,0,1]
	v_pk_fma_f32 v[4:5], v[106:107], v[74:75], v[4:5] op_sel_hi:[1,0,1]
	ds_read_b128 v[52:55], v25 offset:224
	ds_read_b128 v[56:59], v25 offset:4320
	ds_read_b128 v[60:63], v25 offset:8416
	ds_read_b128 v[64:67], v25 offset:12512
	s_waitcnt lgkmcnt(0)
	v_mov_b32_e32 v68, v55
	v_mov_b32_e32 v70, v59
	v_mov_b32_e32 v72, v63
	v_mov_b32_e32 v74, v67
	s_waitcnt vmcnt(7)
	v_pk_fma_f32 v[14:15], v[108:109], v[52:53], v[14:15] op_sel_hi:[1,0,1]
	v_pk_fma_f32 v[16:17], v[110:111], v[52:53], v[16:17] op_sel_hi:[1,0,1]
	v_pk_fma_f32 v[10:11], v[108:109], v[56:57], v[10:11] op_sel_hi:[1,0,1]
	v_pk_fma_f32 v[12:13], v[110:111], v[56:57], v[12:13] op_sel_hi:[1,0,1]
	v_pk_fma_f32 v[6:7], v[108:109], v[60:61], v[6:7] op_sel_hi:[1,0,1]
	v_pk_fma_f32 v[8:9], v[110:111], v[60:61], v[8:9] op_sel_hi:[1,0,1]
	v_pk_fma_f32 v[2:3], v[108:109], v[64:65], v[2:3] op_sel_hi:[1,0,1]
	v_pk_fma_f32 v[4:5], v[110:111], v[64:65], v[4:5] op_sel_hi:[1,0,1]
	s_waitcnt vmcnt(6)
	v_pk_fma_f32 v[14:15], v[112:113], v[52:53], v[14:15] op_sel:[0,1,0]
	v_pk_fma_f32 v[16:17], v[114:115], v[52:53], v[16:17] op_sel:[0,1,0]
	v_pk_fma_f32 v[10:11], v[112:113], v[56:57], v[10:11] op_sel:[0,1,0]
	v_pk_fma_f32 v[12:13], v[114:115], v[56:57], v[12:13] op_sel:[0,1,0]
	v_pk_fma_f32 v[6:7], v[112:113], v[60:61], v[6:7] op_sel:[0,1,0]
	v_pk_fma_f32 v[8:9], v[114:115], v[60:61], v[8:9] op_sel:[0,1,0]
	v_pk_fma_f32 v[2:3], v[112:113], v[64:65], v[2:3] op_sel:[0,1,0]
	v_pk_fma_f32 v[4:5], v[114:115], v[64:65], v[4:5] op_sel:[0,1,0]
	s_waitcnt vmcnt(5)
	v_pk_fma_f32 v[14:15], v[116:117], v[54:55], v[14:15] op_sel_hi:[1,0,1]
	v_pk_fma_f32 v[16:17], v[118:119], v[54:55], v[16:17] op_sel_hi:[1,0,1]
	v_pk_fma_f32 v[10:11], v[116:117], v[58:59], v[10:11] op_sel_hi:[1,0,1]
	v_pk_fma_f32 v[12:13], v[118:119], v[58:59], v[12:13] op_sel_hi:[1,0,1]
	v_pk_fma_f32 v[6:7], v[116:117], v[62:63], v[6:7] op_sel_hi:[1,0,1]
	v_pk_fma_f32 v[8:9], v[118:119], v[62:63], v[8:9] op_sel_hi:[1,0,1]
	v_pk_fma_f32 v[2:3], v[116:117], v[66:67], v[2:3] op_sel_hi:[1,0,1]
	v_pk_fma_f32 v[4:5], v[118:119], v[66:67], v[4:5] op_sel_hi:[1,0,1]
	s_waitcnt vmcnt(4)
	v_pk_fma_f32 v[14:15], v[120:121], v[68:69], v[14:15] op_sel_hi:[1,0,1]
	v_pk_fma_f32 v[16:17], v[122:123], v[68:69], v[16:17] op_sel_hi:[1,0,1]
	v_pk_fma_f32 v[10:11], v[120:121], v[70:71], v[10:11] op_sel_hi:[1,0,1]
	v_pk_fma_f32 v[12:13], v[122:123], v[70:71], v[12:13] op_sel_hi:[1,0,1]
	v_pk_fma_f32 v[6:7], v[120:121], v[72:73], v[6:7] op_sel_hi:[1,0,1]
	v_pk_fma_f32 v[8:9], v[122:123], v[72:73], v[8:9] op_sel_hi:[1,0,1]
	v_pk_fma_f32 v[2:3], v[120:121], v[74:75], v[2:3] op_sel_hi:[1,0,1]
	v_pk_fma_f32 v[4:5], v[122:123], v[74:75], v[4:5] op_sel_hi:[1,0,1]
	ds_read_b128 v[52:55], v25 offset:240
	ds_read_b128 v[56:59], v25 offset:4336
	ds_read_b128 v[60:63], v25 offset:8432
	ds_read_b128 v[64:67], v25 offset:12528
	s_waitcnt lgkmcnt(0)
	v_mov_b32_e32 v68, v55
	v_mov_b32_e32 v70, v59
	v_mov_b32_e32 v72, v63
	v_mov_b32_e32 v74, v67
	s_waitcnt vmcnt(3)
	v_pk_fma_f32 v[14:15], v[124:125], v[52:53], v[14:15] op_sel_hi:[1,0,1]
	v_pk_fma_f32 v[16:17], v[126:127], v[52:53], v[16:17] op_sel_hi:[1,0,1]
	v_pk_fma_f32 v[10:11], v[124:125], v[56:57], v[10:11] op_sel_hi:[1,0,1]
	v_pk_fma_f32 v[12:13], v[126:127], v[56:57], v[12:13] op_sel_hi:[1,0,1]
	v_pk_fma_f32 v[6:7], v[124:125], v[60:61], v[6:7] op_sel_hi:[1,0,1]
	v_pk_fma_f32 v[8:9], v[126:127], v[60:61], v[8:9] op_sel_hi:[1,0,1]
	v_pk_fma_f32 v[2:3], v[124:125], v[64:65], v[2:3] op_sel_hi:[1,0,1]
	v_pk_fma_f32 v[4:5], v[126:127], v[64:65], v[4:5] op_sel_hi:[1,0,1]
	s_waitcnt vmcnt(2)
	v_pk_fma_f32 v[14:15], v[128:129], v[52:53], v[14:15] op_sel:[0,1,0]
	v_pk_fma_f32 v[16:17], v[130:131], v[52:53], v[16:17] op_sel:[0,1,0]
	v_pk_fma_f32 v[10:11], v[128:129], v[56:57], v[10:11] op_sel:[0,1,0]
	v_pk_fma_f32 v[12:13], v[130:131], v[56:57], v[12:13] op_sel:[0,1,0]
	v_pk_fma_f32 v[6:7], v[128:129], v[60:61], v[6:7] op_sel:[0,1,0]
	v_pk_fma_f32 v[8:9], v[130:131], v[60:61], v[8:9] op_sel:[0,1,0]
	v_pk_fma_f32 v[2:3], v[128:129], v[64:65], v[2:3] op_sel:[0,1,0]
	v_pk_fma_f32 v[4:5], v[130:131], v[64:65], v[4:5] op_sel:[0,1,0]
	s_waitcnt vmcnt(1)
	v_pk_fma_f32 v[14:15], v[132:133], v[54:55], v[14:15] op_sel_hi:[1,0,1]
	v_pk_fma_f32 v[16:17], v[134:135], v[54:55], v[16:17] op_sel_hi:[1,0,1]
	v_pk_fma_f32 v[10:11], v[132:133], v[58:59], v[10:11] op_sel_hi:[1,0,1]
	v_pk_fma_f32 v[12:13], v[134:135], v[58:59], v[12:13] op_sel_hi:[1,0,1]
	v_pk_fma_f32 v[6:7], v[132:133], v[62:63], v[6:7] op_sel_hi:[1,0,1]
	v_pk_fma_f32 v[8:9], v[134:135], v[62:63], v[8:9] op_sel_hi:[1,0,1]
	v_pk_fma_f32 v[2:3], v[132:133], v[66:67], v[2:3] op_sel_hi:[1,0,1]
	v_pk_fma_f32 v[4:5], v[134:135], v[66:67], v[4:5] op_sel_hi:[1,0,1]
	s_waitcnt vmcnt(0)
	v_pk_fma_f32 v[14:15], v[136:137], v[68:69], v[14:15] op_sel_hi:[1,0,1]
	v_pk_fma_f32 v[16:17], v[138:139], v[68:69], v[16:17] op_sel_hi:[1,0,1]
	v_pk_fma_f32 v[10:11], v[136:137], v[70:71], v[10:11] op_sel_hi:[1,0,1]
	v_pk_fma_f32 v[12:13], v[138:139], v[70:71], v[12:13] op_sel_hi:[1,0,1]
	v_pk_fma_f32 v[6:7], v[136:137], v[72:73], v[6:7] op_sel_hi:[1,0,1]
	v_pk_fma_f32 v[8:9], v[138:139], v[72:73], v[8:9] op_sel_hi:[1,0,1]
	v_pk_fma_f32 v[2:3], v[136:137], v[74:75], v[2:3] op_sel_hi:[1,0,1]
	v_pk_fma_f32 v[4:5], v[138:139], v[74:75], v[4:5] op_sel_hi:[1,0,1]
	v_lshlrev_b32_e32 v21, 2, v21
	v_mul_hi_i32_i24_e32 v27, 0x14000, v21
	v_mul_i32_i24_e32 v26, 0x14000, v21
	v_ashrrev_i32_e32 v25, 31, v24
	v_lshl_add_u64 v[26:27], s[4:5], 0, v[26:27]
	v_lshlrev_b64 v[24:25], 2, v[24:25]
	v_lshl_add_u64 v[26:27], v[26:27], 0, v[24:25]
	global_store_dwordx4 v[26:27], v[14:17], off
	v_add_u32_e32 v19, s17, v19
	v_cmp_lt_i32_e32 vcc, s22, v19
	v_or_b32_e32 v14, 1, v21
	v_mul_hi_i32_i24_e32 v15, 0x14000, v14
	v_mul_i32_i24_e32 v14, 0x14000, v14
	v_lshl_add_u64 v[14:15], s[4:5], 0, v[14:15]
	v_lshl_add_u64 v[14:15], v[14:15], 0, v[24:25]
	global_store_dwordx4 v[14:15], v[10:13], off
	s_or_b64 s[6:7], vcc, s[6:7]
	s_nop 0
	v_or_b32_e32 v10, 2, v21
	v_mul_hi_i32_i24_e32 v11, 0x14000, v10
	v_mul_i32_i24_e32 v10, 0x14000, v10
	v_lshl_add_u64 v[10:11], s[4:5], 0, v[10:11]
	v_lshl_add_u64 v[10:11], v[10:11], 0, v[24:25]
	global_store_dwordx4 v[10:11], v[6:9], off
	s_nop 1
	v_or_b32_e32 v6, 3, v21
	v_mul_hi_i32_i24_e32 v7, 0x14000, v6
	v_mul_i32_i24_e32 v6, 0x14000, v6
	v_lshl_add_u64 v[6:7], s[4:5], 0, v[6:7]
	v_lshl_add_u64 v[6:7], v[6:7], 0, v[24:25]
	global_store_dwordx4 v[6:7], v[2:5], off
	s_andn2_b64 exec, exec, s[6:7]
	s_cbranch_execnz .LBB0_10

.LBB0_760:
	s_or_b64 exec, exec, s[34:35]
	s_ashr_i32 s0, s78, 31
	s_lshr_b32 s0, s0, 28
	s_add_i32 s1, s78, s0
	s_ashr_i32 s2, s1, 4
	s_abs_i32 s3, s2
	s_mul_hi_u32 s4, s3, s73
	s_mul_i32 s5, s4, s40
	ds_bpermute_b32 v1, v145, v147
	s_sub_i32 s3, s3, s5
	s_ashr_i32 s0, s1, 31
	s_add_i32 s5, s4, 1
	s_sub_i32 s6, s3, s40
	s_cmp_ge_u32 s3, s40
	s_cselect_b32 s4, s5, s4
	s_cselect_b32 s3, s6, s3
	s_add_i32 s5, s4, 1
	s_waitcnt lgkmcnt(0)
	v_add_f32_e32 v5, v147, v1
	s_cmp_ge_u32 s3, s40
	v_cmp_gt_f32_e32 vcc, s95, v5
	s_cselect_b32 s3, s5, s4
	s_xor_b32 s3, s3, s0
	v_cndmask_b32_e64 v1, 0, 32, vcc
	v_ldexp_f32 v1, v5, v1
	s_sub_i32 s0, s3, s0
	v_log_f32_e32 v1, v1
	s_mul_i32 s3, s0, s40
	s_and_b32 s1, s1, -16
	s_sub_i32 s3, s2, s3
	s_sub_i32 s2, s78, s1
	v_mov_b32_e32 v2, 0x42000000
	s_ashr_i32 s1, s0, 31
	v_cndmask_b32_e32 v2, 0, v2, vcc
	s_lshl_b64 s[0:1], s[0:1], 13
	s_ashr_i32 s4, s3, 31
	v_sub_f32_e32 v1, v1, v2
	v_ashrrev_i32_e32 v147, 31, v146
	s_add_u32 s0, s0, s3
	v_add_f32_e32 v1, v148, v1
	v_lshlrev_b64 v[2:3], s71, v[146:147]
	s_addc_u32 s1, s1, s4
	v_cndmask_b32_e64 v6, 0, 1, s[24:25]
	v_mov_b32_e32 v4, 0
	v_mul_f32_e32 v1, 0x3f317218, v1
	v_lshl_add_u64 v[2:3], s[0:1], 0, v[2:3]
	v_cmp_ne_u32_e64 s[0:1], 1, v6
	s_andn2_b64 vcc, exec, s[24:25]
	v_mov_b32_e32 v6, 1.0
	s_cbranch_vccnz .LBB0_762
	v_lshlrev_b64 v[6:7], 6, v[2:3]
	s_ashr_i32 s3, s2, 31
	v_lshl_add_u64 v[6:7], s[28:29], 0, v[6:7]
	v_lshl_add_u64 v[6:7], s[2:3], 2, v[6:7]
	global_load_dword v4, v[6:7], off
	v_lshlrev_b64 v[220:221], 11, v[2:3]
	s_lshl_b32 s4, s2, 6
	v_lshl_add_u64 v[220:221], s[26:27], 0, v[220:221]
	s_ashr_i32 s5, s4, 31
	v_lshlrev_b32_e32 v222, 1, v144
	v_lshl_add_u64 v[220:221], s[4:5], 1, v[220:221]
	v_mad_u64_u32 v[220:221], vcc, v222, 1, v[220:221]
	global_load_dwordx2 v[236:237], v[220:221], off nt
	global_load_dwordx2 v[238:239], v[220:221], off offset:16 nt
	global_load_dwordx2 v[240:241], v[220:221], off offset:32 nt
	global_load_dwordx2 v[242:243], v[220:221], off offset:48 nt
	global_load_dwordx2 v[244:245], v[220:221], off offset:64 nt
	global_load_dwordx2 v[246:247], v[220:221], off offset:80 nt
	global_load_dwordx2 v[248:249], v[220:221], off offset:96 nt
	global_load_dwordx2 v[250:251], v[220:221], off offset:112 nt
	v_max_f32_e32 v6, v1, v1
	s_mov_b32 s3, 0x3f317217
	s_waitcnt vmcnt(0)
	v_max_f32_e32 v7, v4, v4
	v_max_f32_e32 v6, v7, v6
	v_sub_f32_e32 v7, v4, v6
	v_sub_f32_e32 v8, v1, v6
	v_mul_f32_e32 v7, 0x3fb8aa3b, v7
	v_mul_f32_e32 v8, 0x3fb8aa3b, v8
	v_exp_f32_e32 v7, v7
	v_exp_f32_e32 v8, v8
	s_nop 0
	v_add_f32_e32 v7, v7, v8
	v_cmp_gt_f32_e32 vcc, s95, v7
	s_nop 1
	v_cndmask_b32_e64 v8, 0, 32, vcc
	v_ldexp_f32 v7, v7, v8
	v_log_f32_e32 v7, v7
	v_mov_b32_e32 v8, 0x41b17218
	v_cndmask_b32_e32 v8, 0, v8, vcc
	v_mul_f32_e32 v9, 0x3f317217, v7
	v_fma_f32 v9, v7, s3, -v9
	v_fmac_f32_e32 v9, 0x3377d1cf, v7
	s_mov_b32 s3, 0x7f800000
	v_fmac_f32_e32 v9, 0x3f317217, v7
	v_cmp_lt_f32_e64 vcc, |v7|, s3
	s_nop 1
	v_cndmask_b32_e32 v7, v7, v9, vcc
	v_sub_f32_e32 v7, v7, v8
	v_add_f32_e32 v7, v6, v7
	v_sub_f32_e32 v4, v4, v7
	v_sub_f32_e32 v1, v1, v7
	v_mul_f32_e32 v4, 0x3fb8aa3b, v4
	v_mul_f32_e32 v1, 0x3fb8aa3b, v1
	v_exp_f32_e32 v4, v4
	v_exp_f32_e32 v6, v1
	v_mov_b32_e32 v1, v7

.LBB0_931:
	v_ashrrev_i32_e32 v24, 13, v1
	s_waitcnt lgkmcnt(0)
	v_mul_hi_i32_i24_e32 v25, 0x14000, v24
	v_mul_i32_i24_e32 v24, 0x14000, v24
	v_lshl_add_u64 v[24:25], s[2:3], 0, v[24:25]
	s_mov_b64 s[0:1], 0x1000
	v_lshl_add_u64 v[48:49], v[24:25], 0, s[0:1]
	v_lshl_add_u64 v[24:25], v[2:3], 2, v[48:49]
	global_load_dwordx4 v[24:27], v[24:25], off
	s_nop 0
	global_load_dwordx4 v[28:31], v[4:5], off
	global_load_dwordx4 v[32:35], v[14:15], off offset:-2048 nt
	global_load_dwordx4 v[36:39], v[14:15], off offset:-1024 nt
	global_load_dwordx4 v[40:43], v[14:15], off nt
	global_load_dwordx4 v[44:47], v[14:15], off offset:1024 nt
	v_lshl_add_u64 v[50:51], v[6:7], 2, v[48:49]
	s_waitcnt vmcnt(0)
	v_pk_add_f32 v[24:25], v[24:25], 1.0 op_sel_hi:[1,0]
	v_pk_add_f32 v[26:27], v[26:27], 1.0 op_sel_hi:[1,0]
	v_pk_mul_f32 v[24:25], v[28:29], v[24:25]
	v_pk_mul_f32 v[26:27], v[30:31], v[26:27]
	v_pk_mul_f32 v[24:25], v[32:33], v[24:25]
	v_pk_mul_f32 v[26:27], v[34:35], v[26:27]
	v_cvt_pk_bf16_f32 v24, v24, v25
	v_cvt_pk_bf16_f32 v25, v26, v27
	global_store_dwordx2 v[16:17], v[24:25], off offset:-1024
	global_load_dwordx4 v[24:27], v[50:51], off
	s_nop 0
	global_load_dwordx4 v[28:31], v[4:5], off offset:1024
	v_lshl_add_u64 v[50:51], v[8:9], 2, v[48:49]
	v_lshl_add_u64 v[48:49], v[10:11], 2, v[48:49]
	s_waitcnt vmcnt(1)
	v_pk_add_f32 v[24:25], v[24:25], 1.0 op_sel_hi:[1,0]
	v_pk_add_f32 v[26:27], v[26:27], 1.0 op_sel_hi:[1,0]
	s_waitcnt vmcnt(0)
	v_pk_mul_f32 v[24:25], v[28:29], v[24:25]
	v_pk_mul_f32 v[26:27], v[30:31], v[26:27]
	v_pk_mul_f32 v[24:25], v[36:37], v[24:25]
	v_pk_mul_f32 v[26:27], v[38:39], v[26:27]
	v_cvt_pk_bf16_f32 v24, v24, v25
	v_cvt_pk_bf16_f32 v25, v26, v27
	global_store_dwordx2 v[16:17], v[24:25], off offset:-512
	global_load_dwordx4 v[24:27], v[50:51], off
	s_nop 0
	global_load_dwordx4 v[28:31], v[4:5], off offset:2048
	s_waitcnt vmcnt(1)
	v_pk_add_f32 v[24:25], v[24:25], 1.0 op_sel_hi:[1,0]
	v_pk_add_f32 v[26:27], v[26:27], 1.0 op_sel_hi:[1,0]
	s_waitcnt vmcnt(0)
	v_pk_mul_f32 v[24:25], v[28:29], v[24:25]
	v_pk_mul_f32 v[26:27], v[30:31], v[26:27]
	v_pk_mul_f32 v[24:25], v[40:41], v[24:25]
	v_pk_mul_f32 v[26:27], v[42:43], v[26:27]
	v_cvt_pk_bf16_f32 v24, v24, v25
	v_cvt_pk_bf16_f32 v25, v26, v27
	global_store_dwordx2 v[16:17], v[24:25], off
	global_load_dwordx4 v[26:29], v[48:49], off
	s_nop 0
	global_load_dwordx4 v[48:51], v[4:5], off offset:3072
	v_mul_f32_e32 v24, v33, v33
	v_mul_f32_e32 v25, v37, v37
	v_mul_f32_e32 v30, v41, v41
	v_fmac_f32_e32 v24, v32, v32
	v_fmac_f32_e32 v25, v36, v36
	v_mul_f32_e32 v31, v45, v45
	v_fmac_f32_e32 v30, v40, v40
	v_fmac_f32_e32 v24, v34, v34
	v_fmac_f32_e32 v25, v38, v38
	v_fmac_f32_e32 v31, v44, v44
	v_fmac_f32_e32 v30, v42, v42
	v_fmac_f32_e32 v24, v35, v35
	v_fmac_f32_e32 v25, v39, v39
	v_fmac_f32_e32 v31, v46, v46
	v_fmac_f32_e32 v30, v43, v43
	v_add_f32_e32 v24, v24, v25
	v_fmac_f32_e32 v31, v47, v47
	v_add_f32_e32 v24, v24, v30
	v_add_f32_e32 v24, v24, v31
	ds_bpermute_b32 v25, v18, v24
	s_waitcnt lgkmcnt(0)
	v_add_f32_e32 v24, v24, v25
	ds_bpermute_b32 v25, v19, v24
	s_waitcnt lgkmcnt(0)
	v_add_f32_e32 v24, v24, v25
	ds_bpermute_b32 v25, v20, v24
	s_waitcnt lgkmcnt(0)
	v_add_f32_e32 v24, v24, v25
	ds_bpermute_b32 v25, v21, v24
	s_waitcnt lgkmcnt(0)
	v_add_f32_e32 v24, v24, v25
	ds_bpermute_b32 v25, v22, v24
	s_waitcnt lgkmcnt(0)
	v_add_f32_e32 v24, v24, v25
	ds_bpermute_b32 v25, v23, v24
	s_waitcnt vmcnt(1)
	v_pk_add_f32 v[26:27], v[26:27], 1.0 op_sel_hi:[1,0]
	v_pk_add_f32 v[28:29], v[28:29], 1.0 op_sel_hi:[1,0]
	s_waitcnt vmcnt(0)
	v_pk_mul_f32 v[26:27], v[48:49], v[26:27]
	v_pk_mul_f32 v[28:29], v[50:51], v[28:29]
	v_pk_mul_f32 v[26:27], v[44:45], v[26:27]
	v_pk_mul_f32 v[28:29], v[46:47], v[28:29]
	v_cvt_pk_bf16_f32 v26, v26, v27
	v_cvt_pk_bf16_f32 v27, v28, v29
	global_store_dwordx2 v[16:17], v[26:27], off offset:512
	s_and_saveexec_b64 s[0:1], vcc
	s_cbranch_execz .LBB0_930
	s_waitcnt lgkmcnt(0)
	v_add_f32_e32 v24, v24, v25
	global_store_dword v[12:13], v24, off
	s_branch .LBB0_930
